# sc1 write-through scope on in-proj Z stores (EpiZ), on top of v11
# speedup vs baseline: 1.0003x; 1.0003x over previous
; __device__ __forceinline__ unsigned cvt_pk_bf16(float lo, float hi) { unsigned r; asm volatile("v_cvt_pk_bf16_f32 %0, %1, %2" : "=v"(r) : "v"(lo), "v"(hi)); return r; }
; #define LAS __attribute__((address_space(3)))
; __device__ __forceinline__ float gelu_tanh_f(float x) { const float u = 0.7978845608028654f * (x + 0.044715f * x * x * x); return x * fast_rcp(1.f + fast_exp2(-2.f * LOG2E * u)); }
;     __device__ __forceinline__ void operator()(const f32x4 (&acc)[2][2][4][2], const pg8::Unit& u, int wr, int wc, int fr, int fq) const {
;     ...
;             for (int m = 0; m < 4; ++m) { bf16_t* rowp = Z + (size_t)(row0 + ai * 128 + m * 16) * ldc + col0;
;                 const float rs = rsv[m];
; #pragma unroll
;                 for (int bj = 0; bj < 2; ++bj) { float mm = rs;
;                     if (W) { const f32x4 pp = *(const LAS f32x4*)(part + (lrow0 + ai * 128 + m * 16) * 8 + bj * 4);
;                         const float tot = (W == 128) ? ((pp[0] + pp[1]) + (pp[2] + pp[3])) : (wc < 2 ? pp[0] + pp[1] : pp[2] + pp[3]);
;                         mm = rs * rsqrtf(tot * rs * rs * invW + EPS); }
;                     f32x4 v0 = acc[ai][bj][m][0] * mm * g0, v1 = acc[ai][bj][m][1] * mm * g1;
;                     if (act) {
; #pragma unroll
;                         for (int j = 0; j < 4; ++j) { v0[j] = gelu_tanh_f(v0[j]); v1[j] = gelu_tanh_f(v1[j]); } }
;                     u32x4 w; w.x = cvt_pk_bf16(v0[0], v0[1]); w.y = cvt_pk_bf16(v0[2], v0[3]); w.z = cvt_pk_bf16(v1[0], v1[1]); w.w = cvt_pk_bf16(v1[2], v1[3]);
;                     __builtin_nontemporal_store(w, (u32x4*)(rowp + bj * 128)); } } }
.LBB0_315:
	s_lshl_b32 s0, s0, 8
	s_or_b32 s0, s0, s54
	v_lshl_add_u32 v156, v179, 3, s0
	v_mad_u64_u32 v[166:167], s[0:1], v154, s31, 0
	v_mov_b32_e32 v186, v167
	v_ashrrev_i32_e32 v157, 31, v156
	v_mad_u64_u32 v[186:187], s[0:1], v155, s31, v[186:187]
	v_lshl_add_u64 v[156:157], v[156:157], 1, s[42:43]
	v_mov_b32_e32 v167, v186
	v_cvt_pk_bf16_f32 v186, v140, v141
	v_cvt_pk_bf16_f32 v187, v138, v139
	v_cndmask_b32_e64 v138, 0, 1, s[10:11]
	v_lshl_add_u64 v[166:167], v[166:167], 1, v[156:157]
	s_and_b64 vcc, exec, s[6:7]
	v_cmp_ne_u32_e64 s[10:11], 1, v138
	v_cvt_pk_bf16_f32 v188, v168, v169
	v_cvt_pk_bf16_f32 v189, v170, v171
	global_store_dwordx4 v[166:167], v[186:189], off sc1
	s_cbranch_vccnz .LBB0_325
	s_add_i32 s0, 0, 0x20000
	v_add_u32_e32 v138, s0, v184
	ds_read_b128 v[138:141], v138 offset:16
	s_and_b64 vcc, exec, s[10:11]
	s_mov_b64 s[0:1], -1
	s_cbranch_vccnz .LBB0_322
	s_andn2_b64 vcc, exec, s[34:35]
	s_cbranch_vccnz .LBB0_319
	s_waitcnt lgkmcnt(0)
	v_add_f32_e32 v155, v140, v141
	s_mov_b64 s[0:1], 0

; __device__ __forceinline__ unsigned cvt_pk_bf16(float lo, float hi) { unsigned r; asm volatile("v_cvt_pk_bf16_f32 %0, %1, %2" : "=v"(r) : "v"(lo), "v"(hi)); return r; }
; #define LAS __attribute__((address_space(3)))
; __device__ __forceinline__ float gelu_tanh_f(float x) { const float u = 0.7978845608028654f * (x + 0.044715f * x * x * x); return x * fast_rcp(1.f + fast_exp2(-2.f * LOG2E * u)); }
;     __device__ __forceinline__ void operator()(const f32x4 (&acc)[2][2][4][2], const pg8::Unit& u, int wr, int wc, int fr, int fq) const {
;     ...
;                 for (int bj = 0; bj < 2; ++bj) { float mm = rs;
;                     if (W) { const f32x4 pp = *(const LAS f32x4*)(part + (lrow0 + ai * 128 + m * 16) * 8 + bj * 4);
;                         const float tot = (W == 128) ? ((pp[0] + pp[1]) + (pp[2] + pp[3])) : (wc < 2 ? pp[0] + pp[1] : pp[2] + pp[3]);
;                         mm = rs * rsqrtf(tot * rs * rs * invW + EPS); }
;                     f32x4 v0 = acc[ai][bj][m][0] * mm * g0, v1 = acc[ai][bj][m][1] * mm * g1;
;                     if (act) {
; #pragma unroll
;                         for (int j = 0; j < 4; ++j) { v0[j] = gelu_tanh_f(v0[j]); v1[j] = gelu_tanh_f(v1[j]); } }
;                     u32x4 w; w.x = cvt_pk_bf16(v0[0], v0[1]); w.y = cvt_pk_bf16(v0[2], v0[3]); w.z = cvt_pk_bf16(v1[0], v1[1]); w.w = cvt_pk_bf16(v1[2], v1[3]);
;                     __builtin_nontemporal_store(w, (u32x4*)(rowp + bj * 128)); } } }
.LBB0_327:
	v_cvt_pk_bf16_f32 v136, v136, v137
	v_cvt_pk_bf16_f32 v137, v134, v135
	s_and_b64 vcc, exec, s[6:7]
	v_mov_b32_e32 v134, v162
	v_cvt_pk_bf16_f32 v138, v132, v133
	v_cvt_pk_bf16_f32 v139, v130, v131
	global_store_dwordx4 v[166:167], v[136:139], off offset:256 sc1
	s_cbranch_vccnz .LBB0_337
	s_add_i32 s0, 0, 0x20000
	v_add_u32_e32 v130, s0, v184
	ds_read_b128 v[130:133], v130 offset:512
	s_and_b64 vcc, exec, s[10:11]
	s_mov_b64 s[0:1], -1
	s_cbranch_vccnz .LBB0_334
	s_andn2_b64 vcc, exec, s[34:35]
	s_cbranch_vccnz .LBB0_331
	s_waitcnt lgkmcnt(0)
	v_add_f32_e32 v134, v132, v133
	s_mov_b64 s[0:1], 0

; __device__ __forceinline__ unsigned cvt_pk_bf16(float lo, float hi) { unsigned r; asm volatile("v_cvt_pk_bf16_f32 %0, %1, %2" : "=v"(r) : "v"(lo), "v"(hi)); return r; }
; #define LAS __attribute__((address_space(3)))
; __device__ __forceinline__ float gelu_tanh_f(float x) { const float u = 0.7978845608028654f * (x + 0.044715f * x * x * x); return x * fast_rcp(1.f + fast_exp2(-2.f * LOG2E * u)); }
;     __device__ __forceinline__ void operator()(const f32x4 (&acc)[2][2][4][2], const pg8::Unit& u, int wr, int wc, int fr, int fq) const {
;     ...
;                 for (int bj = 0; bj < 2; ++bj) { float mm = rs;
;                     if (W) { const f32x4 pp = *(const LAS f32x4*)(part + (lrow0 + ai * 128 + m * 16) * 8 + bj * 4);
;                         const float tot = (W == 128) ? ((pp[0] + pp[1]) + (pp[2] + pp[3])) : (wc < 2 ? pp[0] + pp[1] : pp[2] + pp[3]);
;                         mm = rs * rsqrtf(tot * rs * rs * invW + EPS); }
;                     f32x4 v0 = acc[ai][bj][m][0] * mm * g0, v1 = acc[ai][bj][m][1] * mm * g1;
;                     if (act) {
; #pragma unroll
;                         for (int j = 0; j < 4; ++j) { v0[j] = gelu_tanh_f(v0[j]); v1[j] = gelu_tanh_f(v1[j]); } }
;                     u32x4 w; w.x = cvt_pk_bf16(v0[0], v0[1]); w.y = cvt_pk_bf16(v0[2], v0[3]); w.z = cvt_pk_bf16(v1[0], v1[1]); w.w = cvt_pk_bf16(v1[2], v1[3]);
;                     __builtin_nontemporal_store(w, (u32x4*)(rowp + bj * 128)); } } }
.LBB0_339:
	v_add_u32_e32 v134, 16, v154
	v_mad_i64_i32 v[134:135], s[0:1], v134, s31, 0
	v_lshl_add_u64 v[134:135], v[134:135], 1, v[156:157]
	s_and_b64 vcc, exec, s[6:7]
	v_cvt_pk_bf16_f32 v166, v132, v133
	v_cvt_pk_bf16_f32 v167, v130, v131
	v_cvt_pk_bf16_f32 v168, v138, v139
	v_cvt_pk_bf16_f32 v169, v136, v137
	global_store_dwordx4 v[134:135], v[166:169], off sc1
	s_cbranch_vccnz .LBB0_349
	s_add_i32 s0, 0, 0x20000
	v_add_u32_e32 v130, s0, v184
	ds_read_b128 v[130:133], v130 offset:528
	s_and_b64 vcc, exec, s[10:11]
	s_mov_b64 s[0:1], -1
	s_cbranch_vccnz .LBB0_346
	s_andn2_b64 vcc, exec, s[34:35]
	s_cbranch_vccnz .LBB0_343
	s_waitcnt lgkmcnt(0)
	v_add_f32_e32 v136, v132, v133
	s_mov_b64 s[0:1], 0

; __device__ __forceinline__ unsigned cvt_pk_bf16(float lo, float hi) { unsigned r; asm volatile("v_cvt_pk_bf16_f32 %0, %1, %2" : "=v"(r) : "v"(lo), "v"(hi)); return r; }
; #define LAS __attribute__((address_space(3)))
; __device__ __forceinline__ float gelu_tanh_f(float x) { const float u = 0.7978845608028654f * (x + 0.044715f * x * x * x); return x * fast_rcp(1.f + fast_exp2(-2.f * LOG2E * u)); }
;     __device__ __forceinline__ void operator()(const f32x4 (&acc)[2][2][4][2], const pg8::Unit& u, int wr, int wc, int fr, int fq) const {
;     ...
;                 for (int bj = 0; bj < 2; ++bj) { float mm = rs;
;                     if (W) { const f32x4 pp = *(const LAS f32x4*)(part + (lrow0 + ai * 128 + m * 16) * 8 + bj * 4);
;                         const float tot = (W == 128) ? ((pp[0] + pp[1]) + (pp[2] + pp[3])) : (wc < 2 ? pp[0] + pp[1] : pp[2] + pp[3]);
;                         mm = rs * rsqrtf(tot * rs * rs * invW + EPS); }
;                     f32x4 v0 = acc[ai][bj][m][0] * mm * g0, v1 = acc[ai][bj][m][1] * mm * g1;
;                     if (act) {
; #pragma unroll
;                         for (int j = 0; j < 4; ++j) { v0[j] = gelu_tanh_f(v0[j]); v1[j] = gelu_tanh_f(v1[j]); } }
;                     u32x4 w; w.x = cvt_pk_bf16(v0[0], v0[1]); w.y = cvt_pk_bf16(v0[2], v0[3]); w.z = cvt_pk_bf16(v1[0], v1[1]); w.w = cvt_pk_bf16(v1[2], v1[3]);
;                     __builtin_nontemporal_store(w, (u32x4*)(rowp + bj * 128)); } } }
.LBB0_351:
	v_cvt_pk_bf16_f32 v128, v128, v129
	v_cvt_pk_bf16_f32 v129, v126, v127
	s_and_b64 vcc, exec, s[6:7]
	v_mov_b32_e32 v126, v160
	v_cvt_pk_bf16_f32 v130, v124, v125
	v_cvt_pk_bf16_f32 v131, v122, v123
	global_store_dwordx4 v[134:135], v[128:131], off offset:256 sc1
	s_cbranch_vccnz .LBB0_361
	s_add_i32 s0, 0, 0x20000
	v_add_u32_e32 v122, s0, v184
	ds_read_b128 v[122:125], v122 offset:1024
	s_and_b64 vcc, exec, s[10:11]
	s_mov_b64 s[0:1], -1
	s_cbranch_vccnz .LBB0_358
	s_andn2_b64 vcc, exec, s[34:35]
	s_cbranch_vccnz .LBB0_355
	s_waitcnt lgkmcnt(0)
	v_add_f32_e32 v126, v124, v125
	s_mov_b64 s[0:1], 0

; __device__ __forceinline__ unsigned cvt_pk_bf16(float lo, float hi) { unsigned r; asm volatile("v_cvt_pk_bf16_f32 %0, %1, %2" : "=v"(r) : "v"(lo), "v"(hi)); return r; }
; #define LAS __attribute__((address_space(3)))
; __device__ __forceinline__ float gelu_tanh_f(float x) { const float u = 0.7978845608028654f * (x + 0.044715f * x * x * x); return x * fast_rcp(1.f + fast_exp2(-2.f * LOG2E * u)); }
;     __device__ __forceinline__ void operator()(const f32x4 (&acc)[2][2][4][2], const pg8::Unit& u, int wr, int wc, int fr, int fq) const {
;     ...
;                 for (int bj = 0; bj < 2; ++bj) { float mm = rs;
;                     if (W) { const f32x4 pp = *(const LAS f32x4*)(part + (lrow0 + ai * 128 + m * 16) * 8 + bj * 4);
;                         const float tot = (W == 128) ? ((pp[0] + pp[1]) + (pp[2] + pp[3])) : (wc < 2 ? pp[0] + pp[1] : pp[2] + pp[3]);
;                         mm = rs * rsqrtf(tot * rs * rs * invW + EPS); }
;                     f32x4 v0 = acc[ai][bj][m][0] * mm * g0, v1 = acc[ai][bj][m][1] * mm * g1;
;                     if (act) {
; #pragma unroll
;                         for (int j = 0; j < 4; ++j) { v0[j] = gelu_tanh_f(v0[j]); v1[j] = gelu_tanh_f(v1[j]); } }
;                     u32x4 w; w.x = cvt_pk_bf16(v0[0], v0[1]); w.y = cvt_pk_bf16(v0[2], v0[3]); w.z = cvt_pk_bf16(v1[0], v1[1]); w.w = cvt_pk_bf16(v1[2], v1[3]);
;                     __builtin_nontemporal_store(w, (u32x4*)(rowp + bj * 128)); } } }
.LBB0_363:
	v_add_u32_e32 v126, 32, v154
	v_mad_i64_i32 v[126:127], s[0:1], v126, s31, 0
	v_lshl_add_u64 v[126:127], v[126:127], 1, v[156:157]
	s_and_b64 vcc, exec, s[6:7]
	v_cvt_pk_bf16_f32 v132, v124, v125
	v_cvt_pk_bf16_f32 v133, v122, v123
	v_cvt_pk_bf16_f32 v134, v130, v131
	v_cvt_pk_bf16_f32 v135, v128, v129
	global_store_dwordx4 v[126:127], v[132:135], off sc1
	s_cbranch_vccnz .LBB0_373
	s_add_i32 s0, 0, 0x20000
	v_add_u32_e32 v122, s0, v184
	ds_read_b128 v[122:125], v122 offset:1040
	s_and_b64 vcc, exec, s[10:11]
	s_mov_b64 s[0:1], -1
	s_cbranch_vccnz .LBB0_370
	s_andn2_b64 vcc, exec, s[34:35]
	s_cbranch_vccnz .LBB0_367
	s_waitcnt lgkmcnt(0)
	v_add_f32_e32 v128, v124, v125
	s_mov_b64 s[0:1], 0

; __device__ __forceinline__ unsigned cvt_pk_bf16(float lo, float hi) { unsigned r; asm volatile("v_cvt_pk_bf16_f32 %0, %1, %2" : "=v"(r) : "v"(lo), "v"(hi)); return r; }
; #define LAS __attribute__((address_space(3)))
; __device__ __forceinline__ float gelu_tanh_f(float x) { const float u = 0.7978845608028654f * (x + 0.044715f * x * x * x); return x * fast_rcp(1.f + fast_exp2(-2.f * LOG2E * u)); }
;     __device__ __forceinline__ void operator()(const f32x4 (&acc)[2][2][4][2], const pg8::Unit& u, int wr, int wc, int fr, int fq) const {
;     ...
;                 for (int bj = 0; bj < 2; ++bj) { float mm = rs;
;                     if (W) { const f32x4 pp = *(const LAS f32x4*)(part + (lrow0 + ai * 128 + m * 16) * 8 + bj * 4);
;                         const float tot = (W == 128) ? ((pp[0] + pp[1]) + (pp[2] + pp[3])) : (wc < 2 ? pp[0] + pp[1] : pp[2] + pp[3]);
;                         mm = rs * rsqrtf(tot * rs * rs * invW + EPS); }
;                     f32x4 v0 = acc[ai][bj][m][0] * mm * g0, v1 = acc[ai][bj][m][1] * mm * g1;
;                     if (act) {
; #pragma unroll
;                         for (int j = 0; j < 4; ++j) { v0[j] = gelu_tanh_f(v0[j]); v1[j] = gelu_tanh_f(v1[j]); } }
;                     u32x4 w; w.x = cvt_pk_bf16(v0[0], v0[1]); w.y = cvt_pk_bf16(v0[2], v0[3]); w.z = cvt_pk_bf16(v1[0], v1[1]); w.w = cvt_pk_bf16(v1[2], v1[3]);
;                     __builtin_nontemporal_store(w, (u32x4*)(rowp + bj * 128)); } } }
.LBB0_375:
	v_cvt_pk_bf16_f32 v120, v120, v121
	v_cvt_pk_bf16_f32 v121, v118, v119
	s_and_b64 vcc, exec, s[6:7]
	v_mov_b32_e32 v118, v0
	v_cvt_pk_bf16_f32 v122, v116, v117
	v_cvt_pk_bf16_f32 v123, v114, v115
	global_store_dwordx4 v[126:127], v[120:123], off offset:256 sc1
	s_cbranch_vccnz .LBB0_385
	s_add_i32 s0, 0, 0x20000
	v_add_u32_e32 v114, s0, v184
	ds_read_b128 v[114:117], v114 offset:1536
	s_and_b64 vcc, exec, s[10:11]
	s_mov_b64 s[0:1], -1
	s_cbranch_vccnz .LBB0_382
	s_andn2_b64 vcc, exec, s[34:35]
	s_cbranch_vccnz .LBB0_379
	s_waitcnt lgkmcnt(0)
	v_add_f32_e32 v118, v116, v117
	s_mov_b64 s[0:1], 0

; __device__ __forceinline__ unsigned cvt_pk_bf16(float lo, float hi) { unsigned r; asm volatile("v_cvt_pk_bf16_f32 %0, %1, %2" : "=v"(r) : "v"(lo), "v"(hi)); return r; }
; #define LAS __attribute__((address_space(3)))
; __device__ __forceinline__ float gelu_tanh_f(float x) { const float u = 0.7978845608028654f * (x + 0.044715f * x * x * x); return x * fast_rcp(1.f + fast_exp2(-2.f * LOG2E * u)); }
;     __device__ __forceinline__ void operator()(const f32x4 (&acc)[2][2][4][2], const pg8::Unit& u, int wr, int wc, int fr, int fq) const {
;     ...
;                 for (int bj = 0; bj < 2; ++bj) { float mm = rs;
;                     if (W) { const f32x4 pp = *(const LAS f32x4*)(part + (lrow0 + ai * 128 + m * 16) * 8 + bj * 4);
;                         const float tot = (W == 128) ? ((pp[0] + pp[1]) + (pp[2] + pp[3])) : (wc < 2 ? pp[0] + pp[1] : pp[2] + pp[3]);
;                         mm = rs * rsqrtf(tot * rs * rs * invW + EPS); }
;                     f32x4 v0 = acc[ai][bj][m][0] * mm * g0, v1 = acc[ai][bj][m][1] * mm * g1;
;                     if (act) {
; #pragma unroll
;                         for (int j = 0; j < 4; ++j) { v0[j] = gelu_tanh_f(v0[j]); v1[j] = gelu_tanh_f(v1[j]); } }
;                     u32x4 w; w.x = cvt_pk_bf16(v0[0], v0[1]); w.y = cvt_pk_bf16(v0[2], v0[3]); w.z = cvt_pk_bf16(v1[0], v1[1]); w.w = cvt_pk_bf16(v1[2], v1[3]);
;                     __builtin_nontemporal_store(w, (u32x4*)(rowp + bj * 128)); } } }
.LBB0_387:
	v_add_u32_e32 v118, 48, v154
	v_mad_i64_i32 v[118:119], s[0:1], v118, s31, 0
	v_lshl_add_u64 v[118:119], v[118:119], 1, v[156:157]
	s_and_b64 vcc, exec, s[6:7]
	v_cvt_pk_bf16_f32 v124, v116, v117
	v_cvt_pk_bf16_f32 v125, v114, v115
	v_cvt_pk_bf16_f32 v126, v122, v123
	v_cvt_pk_bf16_f32 v127, v120, v121
	global_store_dwordx4 v[118:119], v[124:127], off sc1
	s_cbranch_vccnz .LBB0_397
	s_add_i32 s0, 0, 0x20000
	v_add_u32_e32 v114, s0, v184
	ds_read_b128 v[114:117], v114 offset:1552
	s_and_b64 vcc, exec, s[10:11]
	s_mov_b64 s[0:1], -1
	s_cbranch_vccnz .LBB0_394
	s_andn2_b64 vcc, exec, s[34:35]
	s_cbranch_vccnz .LBB0_391
	s_waitcnt lgkmcnt(0)
	v_add_f32_e32 v120, v116, v117
	s_mov_b64 s[0:1], 0

; __device__ __forceinline__ unsigned cvt_pk_bf16(float lo, float hi) { unsigned r; asm volatile("v_cvt_pk_bf16_f32 %0, %1, %2" : "=v"(r) : "v"(lo), "v"(hi)); return r; }
; #define LAS __attribute__((address_space(3)))
; __device__ __forceinline__ float gelu_tanh_f(float x) { const float u = 0.7978845608028654f * (x + 0.044715f * x * x * x); return x * fast_rcp(1.f + fast_exp2(-2.f * LOG2E * u)); }
;     __device__ __forceinline__ void operator()(const f32x4 (&acc)[2][2][4][2], const pg8::Unit& u, int wr, int wc, int fr, int fq) const {
;     ...
;             for (int m = 0; m < 4; ++m) rsv[m] = ssq ? rsqrtf(ssq[row0 + ai * 128 + m * 16] * (1.f / DM) + EPS) : 1.f;
; #pragma unroll
;             for (int m = 0; m < 4; ++m) { bf16_t* rowp = Z + (size_t)(row0 + ai * 128 + m * 16) * ldc + col0;
;                 const float rs = rsv[m];
; #pragma unroll
;                 for (int bj = 0; bj < 2; ++bj) { float mm = rs;
;                     if (W) { const f32x4 pp = *(const LAS f32x4*)(part + (lrow0 + ai * 128 + m * 16) * 8 + bj * 4);
;                         const float tot = (W == 128) ? ((pp[0] + pp[1]) + (pp[2] + pp[3])) : (wc < 2 ? pp[0] + pp[1] : pp[2] + pp[3]);
;                         mm = rs * rsqrtf(tot * rs * rs * invW + EPS); }
;                     f32x4 v0 = acc[ai][bj][m][0] * mm * g0, v1 = acc[ai][bj][m][1] * mm * g1;
;                     if (act) {
; #pragma unroll
;                         for (int j = 0; j < 4; ++j) { v0[j] = gelu_tanh_f(v0[j]); v1[j] = gelu_tanh_f(v1[j]); } }
;                     u32x4 w; w.x = cvt_pk_bf16(v0[0], v0[1]); w.y = cvt_pk_bf16(v0[2], v0[3]); w.z = cvt_pk_bf16(v1[0], v1[1]); w.w = cvt_pk_bf16(v1[2], v1[3]);
;                     __builtin_nontemporal_store(w, (u32x4*)(rowp + bj * 128)); } } }
.LBB0_399:
	v_cvt_pk_bf16_f32 v112, v112, v113
	v_cvt_pk_bf16_f32 v113, v110, v111
	v_cvt_pk_bf16_f32 v114, v108, v109
	s_nop 0
	v_cvt_pk_bf16_f32 v115, v106, v107
	global_store_dwordx4 v[118:119], v[112:115], off offset:256 sc1
	s_and_b64 vcc, exec, s[12:13]
	s_nop 0
	v_mov_b32_e32 v112, 1.0
	v_mov_b32_e32 v114, 1.0
	s_cbranch_vccz .LBB0_406
	s_and_b64 vcc, exec, s[12:13]
	s_cbranch_vccz .LBB0_407

; __device__ __forceinline__ unsigned cvt_pk_bf16(float lo, float hi) { unsigned r; asm volatile("v_cvt_pk_bf16_f32 %0, %1, %2" : "=v"(r) : "v"(lo), "v"(hi)); return r; }
; #define LAS __attribute__((address_space(3)))
; __device__ __forceinline__ float gelu_tanh_f(float x) { const float u = 0.7978845608028654f * (x + 0.044715f * x * x * x); return x * fast_rcp(1.f + fast_exp2(-2.f * LOG2E * u)); }
;     __device__ __forceinline__ void operator()(const f32x4 (&acc)[2][2][4][2], const pg8::Unit& u, int wr, int wc, int fr, int fq) const {
;     ...
;                 for (int bj = 0; bj < 2; ++bj) { float mm = rs;
;                     if (W) { const f32x4 pp = *(const LAS f32x4*)(part + (lrow0 + ai * 128 + m * 16) * 8 + bj * 4);
;                         const float tot = (W == 128) ? ((pp[0] + pp[1]) + (pp[2] + pp[3])) : (wc < 2 ? pp[0] + pp[1] : pp[2] + pp[3]);
;                         mm = rs * rsqrtf(tot * rs * rs * invW + EPS); }
;                     f32x4 v0 = acc[ai][bj][m][0] * mm * g0, v1 = acc[ai][bj][m][1] * mm * g1;
;                     if (act) {
; #pragma unroll
;                         for (int j = 0; j < 4; ++j) { v0[j] = gelu_tanh_f(v0[j]); v1[j] = gelu_tanh_f(v1[j]); } }
;                     u32x4 w; w.x = cvt_pk_bf16(v0[0], v0[1]); w.y = cvt_pk_bf16(v0[2], v0[3]); w.z = cvt_pk_bf16(v1[0], v1[1]); w.w = cvt_pk_bf16(v1[2], v1[3]);
;                     __builtin_nontemporal_store(w, (u32x4*)(rowp + bj * 128)); } } }
.LBB0_421:
	v_add_u32_e32 v111, 0x80, v154
	v_mad_i64_i32 v[116:117], s[0:1], v111, s31, 0
	v_lshl_add_u64 v[116:117], v[116:117], 1, v[156:157]
	s_and_b64 vcc, exec, s[6:7]
	v_cvt_pk_bf16_f32 v122, v108, v109
	v_cvt_pk_bf16_f32 v123, v106, v107
	v_cvt_pk_bf16_f32 v124, v120, v121
	v_cvt_pk_bf16_f32 v125, v118, v119
	global_store_dwordx4 v[116:117], v[122:125], off sc1
	s_cbranch_vccnz .LBB0_431
	s_add_i32 s0, 0, 0x20000
	v_add_u32_e32 v106, s0, v184
	ds_read_b128 v[106:109], v106 offset:4112
	s_and_b64 vcc, exec, s[10:11]
	s_mov_b64 s[0:1], -1
	s_cbranch_vccnz .LBB0_428
	s_andn2_b64 vcc, exec, s[34:35]
	s_cbranch_vccnz .LBB0_425
	s_waitcnt lgkmcnt(0)
	v_add_f32_e32 v111, v108, v109
	s_mov_b64 s[0:1], 0

; __device__ __forceinline__ unsigned cvt_pk_bf16(float lo, float hi) { unsigned r; asm volatile("v_cvt_pk_bf16_f32 %0, %1, %2" : "=v"(r) : "v"(lo), "v"(hi)); return r; }
; #define LAS __attribute__((address_space(3)))
; __device__ __forceinline__ float gelu_tanh_f(float x) { const float u = 0.7978845608028654f * (x + 0.044715f * x * x * x); return x * fast_rcp(1.f + fast_exp2(-2.f * LOG2E * u)); }
;     __device__ __forceinline__ void operator()(const f32x4 (&acc)[2][2][4][2], const pg8::Unit& u, int wr, int wc, int fr, int fq) const {
;     ...
;                 for (int bj = 0; bj < 2; ++bj) { float mm = rs;
;                     if (W) { const f32x4 pp = *(const LAS f32x4*)(part + (lrow0 + ai * 128 + m * 16) * 8 + bj * 4);
;                         const float tot = (W == 128) ? ((pp[0] + pp[1]) + (pp[2] + pp[3])) : (wc < 2 ? pp[0] + pp[1] : pp[2] + pp[3]);
;                         mm = rs * rsqrtf(tot * rs * rs * invW + EPS); }
;                     f32x4 v0 = acc[ai][bj][m][0] * mm * g0, v1 = acc[ai][bj][m][1] * mm * g1;
;                     if (act) {
; #pragma unroll
;                         for (int j = 0; j < 4; ++j) { v0[j] = gelu_tanh_f(v0[j]); v1[j] = gelu_tanh_f(v1[j]); } }
;                     u32x4 w; w.x = cvt_pk_bf16(v0[0], v0[1]); w.y = cvt_pk_bf16(v0[2], v0[3]); w.z = cvt_pk_bf16(v1[0], v1[1]); w.w = cvt_pk_bf16(v1[2], v1[3]);
;                     __builtin_nontemporal_store(w, (u32x4*)(rowp + bj * 128)); } } }
.LBB0_433:
	v_cvt_pk_bf16_f32 v104, v104, v105
	v_cvt_pk_bf16_f32 v105, v102, v103
	s_and_b64 vcc, exec, s[6:7]
	v_mov_b32_e32 v102, v112
	v_cvt_pk_bf16_f32 v106, v100, v101
	v_cvt_pk_bf16_f32 v107, v98, v99
	global_store_dwordx4 v[116:117], v[104:107], off offset:256 sc1
	s_cbranch_vccnz .LBB0_443
	s_add_i32 s0, 0, 0x20000
	v_add_u32_e32 v98, s0, v184
	ds_read_b128 v[98:101], v98 offset:4608
	s_and_b64 vcc, exec, s[10:11]
	s_mov_b64 s[0:1], -1
	s_cbranch_vccnz .LBB0_440
	s_andn2_b64 vcc, exec, s[34:35]
	s_cbranch_vccnz .LBB0_437
	s_waitcnt lgkmcnt(0)
	v_add_f32_e32 v102, v100, v101
	s_mov_b64 s[0:1], 0

; __device__ __forceinline__ unsigned cvt_pk_bf16(float lo, float hi) { unsigned r; asm volatile("v_cvt_pk_bf16_f32 %0, %1, %2" : "=v"(r) : "v"(lo), "v"(hi)); return r; }
; #define LAS __attribute__((address_space(3)))
; __device__ __forceinline__ float gelu_tanh_f(float x) { const float u = 0.7978845608028654f * (x + 0.044715f * x * x * x); return x * fast_rcp(1.f + fast_exp2(-2.f * LOG2E * u)); }
;     __device__ __forceinline__ void operator()(const f32x4 (&acc)[2][2][4][2], const pg8::Unit& u, int wr, int wc, int fr, int fq) const {
;     ...
;                 for (int bj = 0; bj < 2; ++bj) { float mm = rs;
;                     if (W) { const f32x4 pp = *(const LAS f32x4*)(part + (lrow0 + ai * 128 + m * 16) * 8 + bj * 4);
;                         const float tot = (W == 128) ? ((pp[0] + pp[1]) + (pp[2] + pp[3])) : (wc < 2 ? pp[0] + pp[1] : pp[2] + pp[3]);
;                         mm = rs * rsqrtf(tot * rs * rs * invW + EPS); }
;                     f32x4 v0 = acc[ai][bj][m][0] * mm * g0, v1 = acc[ai][bj][m][1] * mm * g1;
;                     if (act) {
; #pragma unroll
;                         for (int j = 0; j < 4; ++j) { v0[j] = gelu_tanh_f(v0[j]); v1[j] = gelu_tanh_f(v1[j]); } }
;                     u32x4 w; w.x = cvt_pk_bf16(v0[0], v0[1]); w.y = cvt_pk_bf16(v0[2], v0[3]); w.z = cvt_pk_bf16(v1[0], v1[1]); w.w = cvt_pk_bf16(v1[2], v1[3]);
;                     __builtin_nontemporal_store(w, (u32x4*)(rowp + bj * 128)); } } }
.LBB0_445:
	v_add_u32_e32 v102, 0x90, v154
	v_mad_i64_i32 v[102:103], s[0:1], v102, s31, 0
	v_lshl_add_u64 v[102:103], v[102:103], 1, v[156:157]
	s_and_b64 vcc, exec, s[6:7]
	v_cvt_pk_bf16_f32 v114, v100, v101
	v_cvt_pk_bf16_f32 v115, v98, v99
	v_cvt_pk_bf16_f32 v116, v106, v107
	v_cvt_pk_bf16_f32 v117, v104, v105
	global_store_dwordx4 v[102:103], v[114:117], off sc1
	s_cbranch_vccnz .LBB0_455
	s_add_i32 s0, 0, 0x20000
	v_add_u32_e32 v98, s0, v184
	ds_read_b128 v[98:101], v98 offset:4624
	s_and_b64 vcc, exec, s[10:11]
	s_mov_b64 s[0:1], -1
	s_cbranch_vccnz .LBB0_452
	s_andn2_b64 vcc, exec, s[34:35]
	s_cbranch_vccnz .LBB0_449
	s_waitcnt lgkmcnt(0)
	v_add_f32_e32 v104, v100, v101
	s_mov_b64 s[0:1], 0

; __device__ __forceinline__ unsigned cvt_pk_bf16(float lo, float hi) { unsigned r; asm volatile("v_cvt_pk_bf16_f32 %0, %1, %2" : "=v"(r) : "v"(lo), "v"(hi)); return r; }
; #define LAS __attribute__((address_space(3)))
; __device__ __forceinline__ float gelu_tanh_f(float x) { const float u = 0.7978845608028654f * (x + 0.044715f * x * x * x); return x * fast_rcp(1.f + fast_exp2(-2.f * LOG2E * u)); }
;     __device__ __forceinline__ void operator()(const f32x4 (&acc)[2][2][4][2], const pg8::Unit& u, int wr, int wc, int fr, int fq) const {
;     ...
;                 for (int bj = 0; bj < 2; ++bj) { float mm = rs;
;                     if (W) { const f32x4 pp = *(const LAS f32x4*)(part + (lrow0 + ai * 128 + m * 16) * 8 + bj * 4);
;                         const float tot = (W == 128) ? ((pp[0] + pp[1]) + (pp[2] + pp[3])) : (wc < 2 ? pp[0] + pp[1] : pp[2] + pp[3]);
;                         mm = rs * rsqrtf(tot * rs * rs * invW + EPS); }
;                     f32x4 v0 = acc[ai][bj][m][0] * mm * g0, v1 = acc[ai][bj][m][1] * mm * g1;
;                     if (act) {
; #pragma unroll
;                         for (int j = 0; j < 4; ++j) { v0[j] = gelu_tanh_f(v0[j]); v1[j] = gelu_tanh_f(v1[j]); } }
;                     u32x4 w; w.x = cvt_pk_bf16(v0[0], v0[1]); w.y = cvt_pk_bf16(v0[2], v0[3]); w.z = cvt_pk_bf16(v1[0], v1[1]); w.w = cvt_pk_bf16(v1[2], v1[3]);
;                     __builtin_nontemporal_store(w, (u32x4*)(rowp + bj * 128)); } } }
.LBB0_457:
	v_cvt_pk_bf16_f32 v98, v88, v89
	v_cvt_pk_bf16_f32 v99, v86, v87
	s_and_b64 vcc, exec, s[6:7]
	v_mov_b32_e32 v86, v110
	v_cvt_pk_bf16_f32 v100, v84, v85
	v_cvt_pk_bf16_f32 v101, v82, v83
	global_store_dwordx4 v[102:103], v[98:101], off offset:256 sc1
	s_cbranch_vccnz .LBB0_467
	s_add_i32 s0, 0, 0x20000
	v_add_u32_e32 v82, s0, v184
	ds_read_b128 v[82:85], v82 offset:5120
	s_and_b64 vcc, exec, s[10:11]
	s_mov_b64 s[0:1], -1
	s_cbranch_vccnz .LBB0_464
	s_andn2_b64 vcc, exec, s[34:35]
	s_cbranch_vccnz .LBB0_461
	s_waitcnt lgkmcnt(0)
	v_add_f32_e32 v86, v84, v85
	s_mov_b64 s[0:1], 0

; __device__ __forceinline__ unsigned cvt_pk_bf16(float lo, float hi) { unsigned r; asm volatile("v_cvt_pk_bf16_f32 %0, %1, %2" : "=v"(r) : "v"(lo), "v"(hi)); return r; }
; #define LAS __attribute__((address_space(3)))
; __device__ __forceinline__ float gelu_tanh_f(float x) { const float u = 0.7978845608028654f * (x + 0.044715f * x * x * x); return x * fast_rcp(1.f + fast_exp2(-2.f * LOG2E * u)); }
;     __device__ __forceinline__ void operator()(const f32x4 (&acc)[2][2][4][2], const pg8::Unit& u, int wr, int wc, int fr, int fq) const {
;     ...
;                 for (int bj = 0; bj < 2; ++bj) { float mm = rs;
;                     if (W) { const f32x4 pp = *(const LAS f32x4*)(part + (lrow0 + ai * 128 + m * 16) * 8 + bj * 4);
;                         const float tot = (W == 128) ? ((pp[0] + pp[1]) + (pp[2] + pp[3])) : (wc < 2 ? pp[0] + pp[1] : pp[2] + pp[3]);
;                         mm = rs * rsqrtf(tot * rs * rs * invW + EPS); }
;                     f32x4 v0 = acc[ai][bj][m][0] * mm * g0, v1 = acc[ai][bj][m][1] * mm * g1;
;                     if (act) {
; #pragma unroll
;                         for (int j = 0; j < 4; ++j) { v0[j] = gelu_tanh_f(v0[j]); v1[j] = gelu_tanh_f(v1[j]); } }
;                     u32x4 w; w.x = cvt_pk_bf16(v0[0], v0[1]); w.y = cvt_pk_bf16(v0[2], v0[3]); w.z = cvt_pk_bf16(v1[0], v1[1]); w.w = cvt_pk_bf16(v1[2], v1[3]);
;                     __builtin_nontemporal_store(w, (u32x4*)(rowp + bj * 128)); } } }
.LBB0_469:
	v_add_u32_e32 v86, 0xa0, v154
	v_mad_i64_i32 v[86:87], s[0:1], v86, s31, 0
	v_lshl_add_u64 v[86:87], v[86:87], 1, v[156:157]
	s_and_b64 vcc, exec, s[6:7]
	v_cvt_pk_bf16_f32 v100, v84, v85
	v_cvt_pk_bf16_f32 v101, v82, v83
	v_cvt_pk_bf16_f32 v102, v98, v99
	v_cvt_pk_bf16_f32 v103, v88, v89
	global_store_dwordx4 v[86:87], v[100:103], off sc1
	s_cbranch_vccnz .LBB0_479
	s_add_i32 s0, 0, 0x20000
	v_add_u32_e32 v82, s0, v184
	ds_read_b128 v[82:85], v82 offset:5136
	s_and_b64 vcc, exec, s[10:11]
	s_mov_b64 s[0:1], -1
	s_cbranch_vccnz .LBB0_476
	s_andn2_b64 vcc, exec, s[34:35]
	s_cbranch_vccnz .LBB0_473
	s_waitcnt lgkmcnt(0)
	v_add_f32_e32 v88, v84, v85
	s_mov_b64 s[0:1], 0

; __device__ __forceinline__ unsigned cvt_pk_bf16(float lo, float hi) { unsigned r; asm volatile("v_cvt_pk_bf16_f32 %0, %1, %2" : "=v"(r) : "v"(lo), "v"(hi)); return r; }
; #define LAS __attribute__((address_space(3)))
; __device__ __forceinline__ float gelu_tanh_f(float x) { const float u = 0.7978845608028654f * (x + 0.044715f * x * x * x); return x * fast_rcp(1.f + fast_exp2(-2.f * LOG2E * u)); }
;     __device__ __forceinline__ void operator()(const f32x4 (&acc)[2][2][4][2], const pg8::Unit& u, int wr, int wc, int fr, int fq) const {
;     ...
;                 for (int bj = 0; bj < 2; ++bj) { float mm = rs;
;                     if (W) { const f32x4 pp = *(const LAS f32x4*)(part + (lrow0 + ai * 128 + m * 16) * 8 + bj * 4);
;                         const float tot = (W == 128) ? ((pp[0] + pp[1]) + (pp[2] + pp[3])) : (wc < 2 ? pp[0] + pp[1] : pp[2] + pp[3]);
;                         mm = rs * rsqrtf(tot * rs * rs * invW + EPS); }
;                     f32x4 v0 = acc[ai][bj][m][0] * mm * g0, v1 = acc[ai][bj][m][1] * mm * g1;
;                     if (act) {
; #pragma unroll
;                         for (int j = 0; j < 4; ++j) { v0[j] = gelu_tanh_f(v0[j]); v1[j] = gelu_tanh_f(v1[j]); } }
;                     u32x4 w; w.x = cvt_pk_bf16(v0[0], v0[1]); w.y = cvt_pk_bf16(v0[2], v0[3]); w.z = cvt_pk_bf16(v1[0], v1[1]); w.w = cvt_pk_bf16(v1[2], v1[3]);
;                     __builtin_nontemporal_store(w, (u32x4*)(rowp + bj * 128)); } } }
.LBB0_481:
	v_cvt_pk_bf16_f32 v80, v80, v81
	v_cvt_pk_bf16_f32 v81, v78, v79
	s_and_b64 vcc, exec, s[6:7]
	v_mov_b32_e32 v78, v0
	v_cvt_pk_bf16_f32 v82, v76, v77
	v_cvt_pk_bf16_f32 v83, v74, v75
	global_store_dwordx4 v[86:87], v[80:83], off offset:256 sc1
	s_cbranch_vccnz .LBB0_491
	s_add_i32 s0, 0, 0x20000
	v_add_u32_e32 v74, s0, v184
	ds_read_b128 v[74:77], v74 offset:5632
	s_and_b64 vcc, exec, s[10:11]
	s_mov_b64 s[0:1], -1
	s_cbranch_vccnz .LBB0_488
	s_andn2_b64 vcc, exec, s[34:35]
	s_cbranch_vccnz .LBB0_485
	s_waitcnt lgkmcnt(0)
	v_add_f32_e32 v78, v76, v77
	s_mov_b64 s[0:1], 0

; __device__ __forceinline__ unsigned cvt_pk_bf16(float lo, float hi) { unsigned r; asm volatile("v_cvt_pk_bf16_f32 %0, %1, %2" : "=v"(r) : "v"(lo), "v"(hi)); return r; }
; #define LAS __attribute__((address_space(3)))
; __device__ __forceinline__ float gelu_tanh_f(float x) { const float u = 0.7978845608028654f * (x + 0.044715f * x * x * x); return x * fast_rcp(1.f + fast_exp2(-2.f * LOG2E * u)); }
;     __device__ __forceinline__ void operator()(const f32x4 (&acc)[2][2][4][2], const pg8::Unit& u, int wr, int wc, int fr, int fq) const {
;     ...
;                 for (int bj = 0; bj < 2; ++bj) { float mm = rs;
;                     if (W) { const f32x4 pp = *(const LAS f32x4*)(part + (lrow0 + ai * 128 + m * 16) * 8 + bj * 4);
;                         const float tot = (W == 128) ? ((pp[0] + pp[1]) + (pp[2] + pp[3])) : (wc < 2 ? pp[0] + pp[1] : pp[2] + pp[3]);
;                         mm = rs * rsqrtf(tot * rs * rs * invW + EPS); }
;                     f32x4 v0 = acc[ai][bj][m][0] * mm * g0, v1 = acc[ai][bj][m][1] * mm * g1;
;                     if (act) {
; #pragma unroll
;                         for (int j = 0; j < 4; ++j) { v0[j] = gelu_tanh_f(v0[j]); v1[j] = gelu_tanh_f(v1[j]); } }
;                     u32x4 w; w.x = cvt_pk_bf16(v0[0], v0[1]); w.y = cvt_pk_bf16(v0[2], v0[3]); w.z = cvt_pk_bf16(v1[0], v1[1]); w.w = cvt_pk_bf16(v1[2], v1[3]);
;                     __builtin_nontemporal_store(w, (u32x4*)(rowp + bj * 128)); } } }
.LBB0_493:
	v_add_u32_e32 v78, 0xb0, v154
	v_mad_i64_i32 v[78:79], s[0:1], v78, s31, 0
	v_lshl_add_u64 v[78:79], v[78:79], 1, v[156:157]
	s_and_b64 vcc, exec, s[6:7]
	v_cvt_pk_bf16_f32 v84, v76, v77
	v_cvt_pk_bf16_f32 v85, v74, v75
	v_cvt_pk_bf16_f32 v86, v82, v83
	v_cvt_pk_bf16_f32 v87, v80, v81
	global_store_dwordx4 v[78:79], v[84:87], off sc1
	s_cbranch_vccnz .LBB0_503
	s_add_i32 s0, 0, 0x20000
	v_add_u32_e32 v74, s0, v184
	ds_read_b128 v[74:77], v74 offset:5648
	s_and_b64 vcc, exec, s[10:11]
	s_mov_b64 s[0:1], -1
	s_cbranch_vccnz .LBB0_500
	s_andn2_b64 vcc, exec, s[34:35]
	s_cbranch_vccnz .LBB0_497
	s_waitcnt lgkmcnt(0)
	v_add_f32_e32 v80, v76, v77
	s_mov_b64 s[0:1], 0

; __device__ __forceinline__ unsigned cvt_pk_bf16(float lo, float hi) { unsigned r; asm volatile("v_cvt_pk_bf16_f32 %0, %1, %2" : "=v"(r) : "v"(lo), "v"(hi)); return r; }
; #define LAS __attribute__((address_space(3)))
; __device__ __forceinline__ float gelu_tanh_f(float x) { const float u = 0.7978845608028654f * (x + 0.044715f * x * x * x); return x * fast_rcp(1.f + fast_exp2(-2.f * LOG2E * u)); }
;     __device__ __forceinline__ void operator()(const f32x4 (&acc)[2][2][4][2], const pg8::Unit& u, int wr, int wc, int fr, int fq) const {
;     ...
;                 for (int bj = 0; bj < 2; ++bj) { float mm = rs;
;                     if (W) { const f32x4 pp = *(const LAS f32x4*)(part + (lrow0 + ai * 128 + m * 16) * 8 + bj * 4);
;                         const float tot = (W == 128) ? ((pp[0] + pp[1]) + (pp[2] + pp[3])) : (wc < 2 ? pp[0] + pp[1] : pp[2] + pp[3]);
;                         mm = rs * rsqrtf(tot * rs * rs * invW + EPS); }
;                     f32x4 v0 = acc[ai][bj][m][0] * mm * g0, v1 = acc[ai][bj][m][1] * mm * g1;
;                     if (act) {
; #pragma unroll
;                         for (int j = 0; j < 4; ++j) { v0[j] = gelu_tanh_f(v0[j]); v1[j] = gelu_tanh_f(v1[j]); } }
;                     u32x4 w; w.x = cvt_pk_bf16(v0[0], v0[1]); w.y = cvt_pk_bf16(v0[2], v0[3]); w.z = cvt_pk_bf16(v1[0], v1[1]); w.w = cvt_pk_bf16(v1[2], v1[3]);
;                     __builtin_nontemporal_store(w, (u32x4*)(rowp + bj * 128)); } } }
.LBB0_505:
	s_mov_b64 s[6:7], 0
	v_cvt_pk_bf16_f32 v72, v72, v73
	v_cvt_pk_bf16_f32 v73, v70, v71
	v_cvt_pk_bf16_f32 v74, v68, v69
	v_cvt_pk_bf16_f32 v75, v66, v67
	global_store_dwordx4 v[78:79], v[72:75], off offset:256 sc1
